# GEMM tile start: accumulator zeroing with 64 v_mov_b64 instead of 128 v_mov_b32 in four of the GEMM unit loops
# baseline (speedup 1.0000x reference)
; template <class Epi, class Sched, bool ALIGN_EPI = false, bool SP2 = false>
; __device__ __forceinline__ void gemm_phase(PG8_LAS unsigned char* lds, const Gemm g, const Sched& S, const Epi& E) {
;     ...
;         const bool has_next = S.next(ui + 1, nxt);
;         const char* nA = has_next ? (const char*)g.A + (size_t)nxt.pm * tstep : cA; const char* nB = has_next ? (const char*)g.Bt + (size_t)nxt.pn * tstep : cB;
;     ...
; #pragma unroll
;         for (int a = 0; a < 2; ++a)
; #pragma unroll
;             for (int b = 0; b < 2; ++b)
; #pragma unroll
;                 for (int m = 0; m < 4; ++m)
; #pragma unroll
;                     for (int n = 0; n < 2; ++n) acc[a][b][m][n] = (f32x4){0.f, 0.f, 0.f, 0.f};
.LBB0_177:
	s_ashr_i32 s19, s18, 31
	s_lshl_b64 s[8:9], s[18:19], 19
	s_add_u32 s22, s58, s8
	s_addc_u32 s23, s59, s9
	s_and_b64 s[8:9], s[0:1], exec
	s_cselect_b32 s19, s23, s27
	s_cselect_b32 s73, s22, s26
	s_ashr_i32 s15, s14, 31
	s_lshl_b64 s[8:9], s[14:15], 19
	s_add_u32 s8, s30, s8
	s_addc_u32 s9, s39, s9
	s_and_b64 s[36:37], s[0:1], exec
	s_cselect_b32 s15, s9, s25
	s_cselect_b32 s74, s8, s24
	s_add_u32 s75, s24, 0x100
	s_addc_u32 s76, s25, 0
	s_add_u32 s24, s26, 0x40080
	v_mov_b32_e32 v2, 0
	s_addc_u32 s25, s27, 0
	s_mov_b32 s77, -2
	v_mov_b64_e32 v[2:3], 0
	v_mov_b64_e32 v[4:5], 0
	v_mov_b64_e32 v[6:7], 0
	v_mov_b64_e32 v[8:9], 0
	v_mov_b64_e32 v[10:11], 0
	v_mov_b64_e32 v[12:13], 0
	v_mov_b64_e32 v[14:15], 0
	v_mov_b64_e32 v[16:17], 0
	v_mov_b64_e32 v[18:19], 0
	v_mov_b64_e32 v[20:21], 0
	v_mov_b64_e32 v[22:23], 0
	v_mov_b64_e32 v[24:25], 0
	v_mov_b64_e32 v[26:27], 0
	v_mov_b64_e32 v[28:29], 0
	v_mov_b64_e32 v[30:31], 0
	v_mov_b64_e32 v[32:33], 0
	v_mov_b64_e32 v[34:35], 0
	v_mov_b64_e32 v[36:37], 0
	v_mov_b64_e32 v[38:39], 0
	v_mov_b64_e32 v[40:41], 0
	v_mov_b64_e32 v[42:43], 0
	v_mov_b64_e32 v[44:45], 0
	v_mov_b64_e32 v[46:47], 0
	v_mov_b64_e32 v[48:49], 0
	v_mov_b64_e32 v[50:51], 0
	v_mov_b64_e32 v[52:53], 0
	v_mov_b64_e32 v[54:55], 0
	v_mov_b64_e32 v[56:57], 0
	v_mov_b64_e32 v[58:59], 0
	v_mov_b64_e32 v[60:61], 0
	v_mov_b64_e32 v[62:63], 0
	v_mov_b64_e32 v[64:65], 0
	v_mov_b64_e32 v[66:67], 0
	v_mov_b64_e32 v[68:69], 0
	v_mov_b64_e32 v[70:71], 0
	v_mov_b64_e32 v[72:73], 0
	v_mov_b64_e32 v[74:75], 0
	v_mov_b64_e32 v[76:77], 0
	v_mov_b64_e32 v[78:79], 0
	v_mov_b64_e32 v[80:81], 0
	v_mov_b64_e32 v[82:83], 0
	v_mov_b64_e32 v[84:85], 0
	v_mov_b64_e32 v[86:87], 0
	v_mov_b64_e32 v[88:89], 0
	v_mov_b64_e32 v[90:91], 0
	v_mov_b64_e32 v[92:93], 0
	v_mov_b64_e32 v[94:95], 0
	v_mov_b64_e32 v[96:97], 0
	v_mov_b64_e32 v[98:99], 0
	v_mov_b64_e32 v[100:101], 0
	v_mov_b64_e32 v[102:103], 0
	v_mov_b64_e32 v[104:105], 0
	v_mov_b64_e32 v[106:107], 0
	v_mov_b64_e32 v[108:109], 0
	v_mov_b64_e32 v[110:111], 0
	v_mov_b64_e32 v[112:113], 0
	v_mov_b64_e32 v[114:115], 0
	v_mov_b64_e32 v[116:117], 0
	v_mov_b64_e32 v[118:119], 0
	v_mov_b64_e32 v[120:121], 0
	v_mov_b64_e32 v[122:123], 0
	v_mov_b64_e32 v[124:125], 0
	v_mov_b64_e32 v[126:127], 0
	v_mov_b64_e32 v[128:129], 0
	v_mov_b32_e32 v224, s72
	v_lshl_add_u32 v224, v224, 8, s61
	v_and_or_b32 v224, v252, 15, v224
	v_ashrrev_i32_e32 v225, 31, v224
	v_lshl_add_u64 v[226:227], v[224:225], 2, s[12:13]
	global_load_dword v232, v[226:227], off
	global_load_dword v233, v[226:227], off offset:64
	global_load_dword v234, v[226:227], off offset:128
	global_load_dword v235, v[226:227], off offset:192
	global_load_dword v236, v[226:227], off offset:512
	global_load_dword v237, v[226:227], off offset:576
	global_load_dword v238, v[226:227], off offset:640
	global_load_dword v239, v[226:227], off offset:704

; template <class Epi, class Sched, bool ALIGN_EPI = false, bool SP2 = false>
; __device__ __forceinline__ void gemm_phase(PG8_LAS unsigned char* lds, const Gemm g, const Sched& S, const Epi& E) {
;     ...
; #pragma unroll
;         for (int a = 0; a < 2; ++a)
; #pragma unroll
;             for (int b = 0; b < 2; ++b)
; #pragma unroll
;                 for (int m = 0; m < 4; ++m)
; #pragma unroll
;                     for (int n = 0; n < 2; ++n) acc[a][b][m][n] = (f32x4){0.f, 0.f, 0.f, 0.f};
.LBB0_387:
	s_add_u32 s74, s24, 0x100
	v_mov_b32_e32 v2, 0
	s_addc_u32 s75, s25, 0
	s_mov_b32 s76, -2
	v_mov_b64_e32 v[2:3], 0
	v_mov_b64_e32 v[4:5], 0
	v_mov_b64_e32 v[6:7], 0
	v_mov_b64_e32 v[8:9], 0
	v_mov_b64_e32 v[10:11], 0
	v_mov_b64_e32 v[12:13], 0
	v_mov_b64_e32 v[14:15], 0
	v_mov_b64_e32 v[16:17], 0
	v_mov_b64_e32 v[18:19], 0
	v_mov_b64_e32 v[20:21], 0
	v_mov_b64_e32 v[22:23], 0
	v_mov_b64_e32 v[24:25], 0
	v_mov_b64_e32 v[26:27], 0
	v_mov_b64_e32 v[28:29], 0
	v_mov_b64_e32 v[30:31], 0
	v_mov_b64_e32 v[32:33], 0
	v_mov_b64_e32 v[34:35], 0
	v_mov_b64_e32 v[36:37], 0
	v_mov_b64_e32 v[38:39], 0
	v_mov_b64_e32 v[40:41], 0
	v_mov_b64_e32 v[42:43], 0
	v_mov_b64_e32 v[44:45], 0
	v_mov_b64_e32 v[46:47], 0
	v_mov_b64_e32 v[48:49], 0
	v_mov_b64_e32 v[50:51], 0
	v_mov_b64_e32 v[52:53], 0
	v_mov_b64_e32 v[54:55], 0
	v_mov_b64_e32 v[56:57], 0
	v_mov_b64_e32 v[58:59], 0
	v_mov_b64_e32 v[60:61], 0
	v_mov_b64_e32 v[62:63], 0
	v_mov_b64_e32 v[64:65], 0
	v_mov_b64_e32 v[66:67], 0
	v_mov_b64_e32 v[68:69], 0
	v_mov_b64_e32 v[70:71], 0
	v_mov_b64_e32 v[72:73], 0
	v_mov_b64_e32 v[74:75], 0
	v_mov_b64_e32 v[76:77], 0
	v_mov_b64_e32 v[78:79], 0
	v_mov_b64_e32 v[80:81], 0
	v_mov_b64_e32 v[82:83], 0
	v_mov_b64_e32 v[84:85], 0
	v_mov_b64_e32 v[86:87], 0
	v_mov_b64_e32 v[88:89], 0
	v_mov_b64_e32 v[90:91], 0
	v_mov_b64_e32 v[92:93], 0
	v_mov_b64_e32 v[94:95], 0
	v_mov_b64_e32 v[96:97], 0
	v_mov_b64_e32 v[98:99], 0
	v_mov_b64_e32 v[100:101], 0
	v_mov_b64_e32 v[102:103], 0
	v_mov_b64_e32 v[104:105], 0
	v_mov_b64_e32 v[106:107], 0
	v_mov_b64_e32 v[108:109], 0
	v_mov_b64_e32 v[110:111], 0
	v_mov_b64_e32 v[112:113], 0
	v_mov_b64_e32 v[114:115], 0
	v_mov_b64_e32 v[116:117], 0
	v_mov_b64_e32 v[118:119], 0
	v_mov_b64_e32 v[120:121], 0
	v_mov_b64_e32 v[122:123], 0
	v_mov_b64_e32 v[124:125], 0
	v_mov_b64_e32 v[126:127], 0
	v_mov_b64_e32 v[128:129], 0

; template <class Epi, class Sched, bool ALIGN_EPI = false, bool SP2 = false>
; __device__ __forceinline__ void gemm_phase(PG8_LAS unsigned char* lds, const Gemm g, const Sched& S, const Epi& E) {
;     ...
;         const bool has_next = S.next(ui + 1, nxt);
;         const char* nA = has_next ? (const char*)g.A + (size_t)nxt.pm * tstep : cA; const char* nB = has_next ? (const char*)g.Bt + (size_t)nxt.pn * tstep : cB;
;     ...
; #pragma unroll
;         for (int a = 0; a < 2; ++a)
; #pragma unroll
;             for (int b = 0; b < 2; ++b)
; #pragma unroll
;                 for (int m = 0; m < 4; ++m)
; #pragma unroll
;                     for (int n = 0; n < 2; ++n) acc[a][b][m][n] = (f32x4){0.f, 0.f, 0.f, 0.f};
.LBB0_546:
	s_ashr_i32 s23, s22, 31
	s_lshl_b64 s[24:25], s[22:23], 19
	s_add_u32 s24, s58, s24
	s_addc_u32 s25, s59, s25
	s_and_b64 s[26:27], s[0:1], exec
	s_cselect_b32 s5, s25, s39
	s_cselect_b32 s23, s24, s38
	s_ashr_i32 s15, s14, 31
	s_lshl_b64 s[26:27], s[14:15], 19
	s_add_u32 s26, s30, s26
	s_addc_u32 s27, s40, s27
	s_and_b64 s[60:61], s[0:1], exec
	s_cselect_b32 s15, s27, s37
	s_cselect_b32 s73, s26, s36
	s_add_u32 s74, s36, 0x100
	s_addc_u32 s75, s37, 0
	s_add_u32 s60, s38, 0x40080
	v_mov_b32_e32 v2, 0
	s_addc_u32 s61, s39, 0
	s_mov_b32 s76, -2
	v_mov_b64_e32 v[2:3], 0
	v_mov_b64_e32 v[4:5], 0
	v_mov_b64_e32 v[6:7], 0
	v_mov_b64_e32 v[8:9], 0
	v_mov_b64_e32 v[10:11], 0
	v_mov_b64_e32 v[12:13], 0
	v_mov_b64_e32 v[14:15], 0
	v_mov_b64_e32 v[16:17], 0
	v_mov_b64_e32 v[18:19], 0
	v_mov_b64_e32 v[20:21], 0
	v_mov_b64_e32 v[22:23], 0
	v_mov_b64_e32 v[24:25], 0
	v_mov_b64_e32 v[26:27], 0
	v_mov_b64_e32 v[28:29], 0
	v_mov_b64_e32 v[30:31], 0
	v_mov_b64_e32 v[32:33], 0
	v_mov_b64_e32 v[34:35], 0
	v_mov_b64_e32 v[36:37], 0
	v_mov_b64_e32 v[38:39], 0
	v_mov_b64_e32 v[40:41], 0
	v_mov_b64_e32 v[42:43], 0
	v_mov_b64_e32 v[44:45], 0
	v_mov_b64_e32 v[46:47], 0
	v_mov_b64_e32 v[48:49], 0
	v_mov_b64_e32 v[50:51], 0
	v_mov_b64_e32 v[52:53], 0
	v_mov_b64_e32 v[54:55], 0
	v_mov_b64_e32 v[56:57], 0
	v_mov_b64_e32 v[58:59], 0
	v_mov_b64_e32 v[60:61], 0
	v_mov_b64_e32 v[62:63], 0
	v_mov_b64_e32 v[64:65], 0
	v_mov_b64_e32 v[66:67], 0
	v_mov_b64_e32 v[68:69], 0
	v_mov_b64_e32 v[70:71], 0
	v_mov_b64_e32 v[72:73], 0
	v_mov_b64_e32 v[74:75], 0
	v_mov_b64_e32 v[76:77], 0
	v_mov_b64_e32 v[78:79], 0
	v_mov_b64_e32 v[80:81], 0
	v_mov_b64_e32 v[82:83], 0
	v_mov_b64_e32 v[84:85], 0
	v_mov_b64_e32 v[86:87], 0
	v_mov_b64_e32 v[88:89], 0
	v_mov_b64_e32 v[90:91], 0
	v_mov_b64_e32 v[92:93], 0
	v_mov_b64_e32 v[94:95], 0
	v_mov_b64_e32 v[96:97], 0
	v_mov_b64_e32 v[98:99], 0
	v_mov_b64_e32 v[100:101], 0
	v_mov_b64_e32 v[102:103], 0
	v_mov_b64_e32 v[104:105], 0
	v_mov_b64_e32 v[106:107], 0
	v_mov_b64_e32 v[108:109], 0
	v_mov_b64_e32 v[110:111], 0
	v_mov_b64_e32 v[112:113], 0
	v_mov_b64_e32 v[114:115], 0
	v_mov_b64_e32 v[116:117], 0
	v_mov_b64_e32 v[118:119], 0
	v_mov_b64_e32 v[120:121], 0
	v_mov_b64_e32 v[122:123], 0
	v_mov_b64_e32 v[124:125], 0
	v_mov_b64_e32 v[126:127], 0
	v_mov_b64_e32 v[128:129], 0
	v_mov_b32_e32 v224, s52
	v_lshl_add_u32 v224, v224, 8, s65
	v_and_or_b32 v224, v252, 15, v224
	v_ashrrev_i32_e32 v225, 31, v224
	v_lshl_add_u64 v[226:227], v[224:225], 2, s[10:11]
	global_load_dword v232, v[226:227], off
	global_load_dword v233, v[226:227], off offset:64
	global_load_dword v234, v[226:227], off offset:128
	global_load_dword v235, v[226:227], off offset:192
	global_load_dword v236, v[226:227], off offset:512
	global_load_dword v237, v[226:227], off offset:576
	global_load_dword v238, v[226:227], off offset:640
	global_load_dword v239, v[226:227], off offset:704

; template <class Epi, class Sched, bool ALIGN_EPI = false, bool SP2 = false>
; __device__ __forceinline__ void gemm_phase(PG8_LAS unsigned char* lds, const Gemm g, const Sched& S, const Epi& E) {
;     ...
;     f32x4 acc[2][2][4][2];
; #pragma unroll
;     for (int a = 0; a < 2; ++a)
; #pragma unroll
;         for (int b = 0; b < 2; ++b)
; #pragma unroll
;             for (int m = 0; m < 4; ++m)
; #pragma unroll
;                 for (int n = 0; n < 2; ++n) acc[a][b][m][n] = (f32x4){0.f, 0.f, 0.f, 0.f};
;     ...
; #pragma unroll
;         for (int a = 0; a < 2; ++a)
; #pragma unroll
;             for (int b = 0; b < 2; ++b)
; #pragma unroll
;                 for (int m = 0; m < 4; ++m)
; #pragma unroll
;                     for (int n = 0; n < 2; ++n) acc[a][b][m][n] = (f32x4){0.f, 0.f, 0.f, 0.f};
.LBB0_781:
	v_mov_b32_e32 v125, 0
	s_andn2_b64 vcc, exec, s[14:15]
	v_mov_b32_e32 v124, v125
	v_mov_b32_e32 v123, v125
	v_mov_b32_e32 v122, v125
	v_mov_b32_e32 v129, v125
	v_mov_b32_e32 v128, v125
	v_mov_b32_e32 v127, v125
	v_mov_b32_e32 v126, v125
	v_mov_b32_e32 v113, v125
	v_mov_b32_e32 v112, v125
	v_mov_b32_e32 v111, v125
	v_mov_b32_e32 v110, v125
	v_mov_b32_e32 v109, v125
	v_mov_b32_e32 v108, v125
	v_mov_b32_e32 v107, v125
	v_mov_b32_e32 v106, v125
	v_mov_b32_e32 v97, v125
	v_mov_b32_e32 v96, v125
	v_mov_b32_e32 v95, v125
	v_mov_b32_e32 v94, v125
	v_mov_b32_e32 v93, v125
	v_mov_b32_e32 v92, v125
	v_mov_b32_e32 v91, v125
	v_mov_b32_e32 v90, v125
	v_mov_b32_e32 v81, v125
	v_mov_b32_e32 v80, v125
	v_mov_b32_e32 v79, v125
	v_mov_b32_e32 v78, v125
	v_mov_b32_e32 v77, v125
	v_mov_b32_e32 v76, v125
	v_mov_b32_e32 v75, v125
	v_mov_b32_e32 v74, v125
	v_mov_b32_e32 v121, v125
	v_mov_b32_e32 v120, v125
	v_mov_b32_e32 v119, v125
	v_mov_b32_e32 v118, v125
	v_mov_b32_e32 v117, v125
	v_mov_b32_e32 v116, v125
	v_mov_b32_e32 v115, v125
	v_mov_b32_e32 v114, v125
	v_mov_b32_e32 v105, v125
	v_mov_b32_e32 v104, v125
	v_mov_b32_e32 v103, v125
	v_mov_b32_e32 v102, v125
	v_mov_b32_e32 v101, v125
	v_mov_b32_e32 v100, v125
	v_mov_b32_e32 v99, v125
	v_mov_b32_e32 v98, v125
	v_mov_b32_e32 v89, v125
	v_mov_b32_e32 v88, v125
	v_mov_b32_e32 v87, v125
	v_mov_b32_e32 v86, v125
	v_mov_b32_e32 v85, v125
	v_mov_b32_e32 v84, v125
	v_mov_b32_e32 v83, v125
	v_mov_b32_e32 v82, v125
	v_mov_b32_e32 v73, v125
	v_mov_b32_e32 v72, v125
	v_mov_b32_e32 v71, v125
	v_mov_b32_e32 v70, v125
	v_mov_b32_e32 v69, v125
	v_mov_b32_e32 v68, v125
	v_mov_b32_e32 v67, v125
	v_mov_b32_e32 v66, v125
	v_mov_b32_e32 v65, v125
	v_mov_b32_e32 v64, v125
	v_mov_b32_e32 v63, v125
	v_mov_b32_e32 v62, v125
	v_mov_b32_e32 v61, v125
	v_mov_b32_e32 v60, v125
	v_mov_b32_e32 v59, v125
	v_mov_b32_e32 v58, v125
	v_mov_b32_e32 v49, v125
	v_mov_b32_e32 v48, v125
	v_mov_b32_e32 v47, v125
	v_mov_b32_e32 v46, v125
	v_mov_b32_e32 v45, v125
	v_mov_b32_e32 v44, v125
	v_mov_b32_e32 v43, v125
	v_mov_b32_e32 v42, v125
	v_mov_b32_e32 v33, v125
	v_mov_b32_e32 v32, v125
	v_mov_b32_e32 v31, v125
	v_mov_b32_e32 v30, v125
	v_mov_b32_e32 v29, v125
	v_mov_b32_e32 v28, v125
	v_mov_b32_e32 v27, v125
	v_mov_b32_e32 v26, v125
	v_mov_b32_e32 v17, v125
	v_mov_b32_e32 v16, v125
	v_mov_b32_e32 v15, v125
	v_mov_b32_e32 v14, v125
	v_mov_b32_e32 v13, v125
	v_mov_b32_e32 v12, v125
	v_mov_b32_e32 v11, v125
	v_mov_b32_e32 v10, v125
	v_mov_b32_e32 v57, v125
	v_mov_b32_e32 v56, v125
	v_mov_b32_e32 v55, v125
	v_mov_b32_e32 v54, v125
	v_mov_b32_e32 v53, v125
	v_mov_b32_e32 v52, v125
	v_mov_b32_e32 v51, v125
	v_mov_b32_e32 v50, v125
	v_mov_b32_e32 v41, v125
	v_mov_b32_e32 v40, v125
	v_mov_b32_e32 v39, v125
	v_mov_b32_e32 v38, v125
	v_mov_b32_e32 v37, v125
	v_mov_b32_e32 v36, v125
	v_mov_b32_e32 v35, v125
	v_mov_b32_e32 v34, v125
	v_mov_b32_e32 v25, v125
	v_mov_b32_e32 v24, v125
	v_mov_b32_e32 v23, v125
	v_mov_b32_e32 v22, v125
	v_mov_b32_e32 v21, v125
	v_mov_b32_e32 v20, v125
	v_mov_b32_e32 v19, v125
	v_mov_b32_e32 v18, v125
	v_mov_b32_e32 v9, v125
	v_mov_b32_e32 v8, v125
	v_mov_b32_e32 v7, v125
	v_mov_b32_e32 v6, v125
	v_mov_b32_e32 v5, v125
	v_mov_b32_e32 v4, v125
	v_mov_b32_e32 v3, v125
	v_mov_b32_e32 v2, v125
	s_cbranch_vccnz .LBB0_785
	s_add_u32 s40, s36, 0x100
	s_addc_u32 s41, s37, 0
	s_add_u32 s4, s38, 0x80
	v_mov_b32_e32 v2, 0
	s_mov_b32 vcc_hi, s87
	s_addc_u32 s5, s39, 0
	s_mov_b32 s36, 0
	v_mov_b64_e32 v[2:3], 0
	v_mov_b64_e32 v[4:5], 0
	v_mov_b64_e32 v[6:7], 0
	v_mov_b64_e32 v[8:9], 0
	v_mov_b64_e32 v[10:11], 0
	v_mov_b64_e32 v[12:13], 0
	v_mov_b64_e32 v[14:15], 0
	v_mov_b64_e32 v[16:17], 0
	v_mov_b64_e32 v[18:19], 0
	v_mov_b64_e32 v[20:21], 0
	v_mov_b64_e32 v[22:23], 0
	v_mov_b64_e32 v[24:25], 0
	v_mov_b64_e32 v[26:27], 0
	v_mov_b64_e32 v[28:29], 0
	v_mov_b64_e32 v[30:31], 0
	v_mov_b64_e32 v[32:33], 0
	v_mov_b64_e32 v[34:35], 0
	v_mov_b64_e32 v[36:37], 0
	v_mov_b64_e32 v[38:39], 0
	v_mov_b64_e32 v[40:41], 0
	v_mov_b64_e32 v[42:43], 0
	v_mov_b64_e32 v[44:45], 0
	v_mov_b64_e32 v[46:47], 0
	v_mov_b64_e32 v[48:49], 0
	v_mov_b64_e32 v[50:51], 0
	v_mov_b64_e32 v[52:53], 0
	v_mov_b64_e32 v[54:55], 0
	v_mov_b64_e32 v[56:57], 0
	v_mov_b64_e32 v[58:59], 0
	v_mov_b64_e32 v[60:61], 0
	v_mov_b64_e32 v[62:63], 0
	v_mov_b64_e32 v[64:65], 0
	v_mov_b64_e32 v[66:67], 0
	v_mov_b64_e32 v[68:69], 0
	v_mov_b64_e32 v[70:71], 0
	v_mov_b64_e32 v[72:73], 0
	v_mov_b64_e32 v[74:75], 0
	v_mov_b64_e32 v[76:77], 0
	v_mov_b64_e32 v[78:79], 0
	v_mov_b64_e32 v[80:81], 0
	v_mov_b64_e32 v[82:83], 0
	v_mov_b64_e32 v[84:85], 0
	v_mov_b64_e32 v[86:87], 0
	v_mov_b64_e32 v[88:89], 0
	v_mov_b64_e32 v[90:91], 0
	v_mov_b64_e32 v[92:93], 0
	v_mov_b64_e32 v[94:95], 0
	v_mov_b64_e32 v[96:97], 0
	v_mov_b64_e32 v[98:99], 0
	v_mov_b64_e32 v[100:101], 0
	v_mov_b64_e32 v[102:103], 0
	v_mov_b64_e32 v[104:105], 0
	v_mov_b64_e32 v[106:107], 0
	v_mov_b64_e32 v[108:109], 0
	v_mov_b64_e32 v[110:111], 0
	v_mov_b64_e32 v[112:113], 0
	v_mov_b64_e32 v[114:115], 0
	v_mov_b64_e32 v[116:117], 0
	v_mov_b64_e32 v[118:119], 0
	v_mov_b64_e32 v[120:121], 0
	v_mov_b64_e32 v[122:123], 0
	v_mov_b64_e32 v[124:125], 0
	v_mov_b64_e32 v[126:127], 0
	v_mov_b64_e32 v[128:129], 0
